# in-proj epilogue: 8 per-row rstd loads hoisted (one wait instead of 8 drains); FoX scan moved to workgroups 0-31; on top of barrier removal + P.V counted waits
# speedup vs baseline: 1.0107x; 1.0078x over previous
.LBB0_241:
	v_ashrrev_i32_e32 v151, 31, v150
	v_lshl_add_u64 v[154:155], v[150:151], 2, s[66:67]
	global_load_dword v152, v[154:155], off
	global_load_dword v200, v[154:155], off offset:64
	global_load_dword v201, v[154:155], off offset:128
	global_load_dword v202, v[154:155], off offset:192
	global_load_dword v203, v[154:155], off offset:512
	global_load_dword v204, v[154:155], off offset:576
	global_load_dword v205, v[154:155], off offset:640
	global_load_dword v206, v[154:155], off offset:704
	v_cndmask_b32_e64 v153, 0, 1, s[60:61]
	v_cmp_ne_u32_e64 s[6:7], 1, v153
	s_andn2_b64 vcc, exec, s[60:61]
	s_waitcnt vmcnt(0)
	v_mul_f32_e32 v153, 0x3e0293ee, v152
	v_cndmask_b32_e64 v170, v152, v153, s[56:57]
	v_pk_mul_f32 v[162:163], v[126:127], v[170:171] op_sel_hi:[1,0]
	v_pk_mul_f32 v[164:165], v[124:125], v[170:171] op_sel_hi:[1,0]
	v_pk_mul_f32 v[156:157], v[122:123], v[170:171] op_sel_hi:[1,0]
	v_pk_mul_f32 v[158:159], v[120:121], v[170:171] op_sel_hi:[1,0]
	v_mov_b32_e32 v166, v164
	v_mov_b32_e32 v167, v165
	v_mov_b32_e32 v172, v162
	v_mov_b32_e32 v173, v163
	v_mov_b32_e32 v168, v158
	v_mov_b32_e32 v169, v159
	v_mov_b32_e32 v176, v156
	v_mov_b32_e32 v177, v157
	s_cbranch_vccnz .LBB0_243
	v_mul_f32_e32 v153, 0xbfb8aa3b, v158
	v_exp_f32_e32 v153, v153
	v_mul_f32_e32 v166, 0xbfb8aa3b, v165
	v_mul_f32_e32 v167, 0xbfb8aa3b, v159
	v_exp_f32_e32 v166, v166
	v_exp_f32_e32 v167, v167
	v_add_f32_e32 v153, 1.0, v153
	v_rcp_f32_e32 v168, v153
	v_add_f32_e32 v153, 1.0, v166
	v_add_f32_e32 v166, 1.0, v167
	v_mul_f32_e32 v167, 0xbfb8aa3b, v162
	v_exp_f32_e32 v167, v167
	v_mul_f32_e32 v169, 0xbfb8aa3b, v156
	v_exp_f32_e32 v171, v169
	v_rcp_f32_e32 v169, v166
	v_add_f32_e32 v166, 1.0, v167
	v_mul_f32_e32 v167, 0xbfb8aa3b, v163
	v_mul_f32_e32 v152, 0xbfb8aa3b, v164
	v_rcp_f32_e32 v172, v166
	v_add_f32_e32 v166, 1.0, v171
	v_exp_f32_e32 v167, v167
	v_mul_f32_e32 v171, 0xbfb8aa3b, v157
	v_exp_f32_e32 v152, v152
	v_exp_f32_e32 v171, v171
	v_rcp_f32_e32 v174, v166
	v_add_f32_e32 v166, 1.0, v167
	v_add_f32_e32 v152, 1.0, v152
	v_rcp_f32_e32 v173, v166
	v_add_f32_e32 v166, 1.0, v171
	v_rcp_f32_e32 v152, v152
	v_rcp_f32_e32 v153, v153
	v_rcp_f32_e32 v175, v166
	v_pk_mul_f32 v[168:169], v[158:159], v[168:169]
	v_pk_mul_f32 v[172:173], v[162:163], v[172:173]
	v_pk_mul_f32 v[166:167], v[164:165], v[152:153]
	v_pk_mul_f32 v[176:177], v[156:157], v[174:175]

.LBB0_249:
	v_mov_b32_e32 v151, v200
	s_and_b64 vcc, exec, s[6:7]
	s_nop 0
	v_mul_f32_e32 v156, 0x3e0293ee, v151
	v_cndmask_b32_e64 v172, v151, v156, s[56:57]
	v_pk_mul_f32 v[162:163], v[110:111], v[172:173] op_sel_hi:[1,0]
	v_pk_mul_f32 v[164:165], v[108:109], v[172:173] op_sel_hi:[1,0]
	s_waitcnt lgkmcnt(0)
	v_pk_mul_f32 v[156:157], v[106:107], v[172:173] op_sel_hi:[1,0]
	v_pk_mul_f32 v[158:159], v[104:105], v[172:173] op_sel_hi:[1,0]
	v_mov_b32_e32 v168, v164
	v_mov_b32_e32 v169, v165
	v_mov_b32_e32 v174, v162
	v_mov_b32_e32 v175, v163
	v_mov_b32_e32 v170, v158
	v_mov_b32_e32 v171, v159
	v_mov_b32_e32 v178, v156
	v_mov_b32_e32 v179, v157
	s_cbranch_vccnz .LBB0_251
	v_mul_f32_e32 v151, 0xbfb8aa3b, v164
	v_exp_f32_e32 v151, v151
	v_mul_f32_e32 v166, 0xbfb8aa3b, v158
	v_exp_f32_e32 v166, v166
	v_mul_f32_e32 v168, 0xbfb8aa3b, v159
	v_add_f32_e32 v151, 1.0, v151
	v_exp_f32_e32 v168, v168
	v_add_f32_e32 v167, 1.0, v166
	v_rcp_f32_e32 v166, v151
	v_mul_f32_e32 v151, 0xbfb8aa3b, v165
	v_exp_f32_e32 v151, v151
	v_rcp_f32_e32 v170, v167
	v_mul_f32_e32 v169, 0xbfb8aa3b, v156
	v_exp_f32_e32 v169, v169
	v_add_f32_e32 v151, 1.0, v151
	v_rcp_f32_e32 v167, v151
	v_add_f32_e32 v151, 1.0, v168
	v_mul_f32_e32 v168, 0xbfb8aa3b, v162
	v_exp_f32_e32 v168, v168
	v_rcp_f32_e32 v171, v151
	v_add_f32_e32 v151, 1.0, v168
	v_mul_f32_e32 v168, 0xbfb8aa3b, v163
	v_rcp_f32_e32 v174, v151
	v_add_f32_e32 v151, 1.0, v169
	v_exp_f32_e32 v168, v168
	v_mul_f32_e32 v169, 0xbfb8aa3b, v157
	v_exp_f32_e32 v169, v169
	v_rcp_f32_e32 v176, v151
	v_add_f32_e32 v151, 1.0, v168
	v_rcp_f32_e32 v175, v151
	v_add_f32_e32 v151, 1.0, v169
	v_rcp_f32_e32 v177, v151
	v_pk_mul_f32 v[168:169], v[164:165], v[166:167]
	v_pk_mul_f32 v[170:171], v[158:159], v[170:171]
	v_pk_mul_f32 v[174:175], v[162:163], v[174:175]
	v_pk_mul_f32 v[178:179], v[156:157], v[176:177]

.LBB0_257:
	v_mov_b32_e32 v151, v201
	s_and_b64 vcc, exec, s[6:7]
	s_nop 0
	v_mul_f32_e32 v156, 0x3e0293ee, v151
	v_cndmask_b32_e64 v172, v151, v156, s[56:57]
	v_pk_mul_f32 v[162:163], v[94:95], v[172:173] op_sel_hi:[1,0]
	v_pk_mul_f32 v[164:165], v[92:93], v[172:173] op_sel_hi:[1,0]
	s_waitcnt lgkmcnt(0)
	v_pk_mul_f32 v[156:157], v[90:91], v[172:173] op_sel_hi:[1,0]
	v_pk_mul_f32 v[158:159], v[88:89], v[172:173] op_sel_hi:[1,0]
	v_mov_b32_e32 v168, v164
	v_mov_b32_e32 v169, v165
	v_mov_b32_e32 v174, v162
	v_mov_b32_e32 v175, v163
	v_mov_b32_e32 v170, v158
	v_mov_b32_e32 v171, v159
	v_mov_b32_e32 v178, v156
	v_mov_b32_e32 v179, v157
	s_cbranch_vccnz .LBB0_259
	v_mul_f32_e32 v151, 0xbfb8aa3b, v164
	v_exp_f32_e32 v151, v151
	v_mul_f32_e32 v166, 0xbfb8aa3b, v158
	v_exp_f32_e32 v166, v166
	v_mul_f32_e32 v168, 0xbfb8aa3b, v159
	v_add_f32_e32 v151, 1.0, v151
	v_exp_f32_e32 v168, v168
	v_add_f32_e32 v167, 1.0, v166
	v_rcp_f32_e32 v166, v151
	v_mul_f32_e32 v151, 0xbfb8aa3b, v165
	v_exp_f32_e32 v151, v151
	v_rcp_f32_e32 v170, v167
	v_mul_f32_e32 v169, 0xbfb8aa3b, v156
	v_exp_f32_e32 v169, v169
	v_add_f32_e32 v151, 1.0, v151
	v_rcp_f32_e32 v167, v151
	v_add_f32_e32 v151, 1.0, v168
	v_mul_f32_e32 v168, 0xbfb8aa3b, v162
	v_exp_f32_e32 v168, v168
	v_rcp_f32_e32 v171, v151
	v_add_f32_e32 v151, 1.0, v168
	v_mul_f32_e32 v168, 0xbfb8aa3b, v163
	v_rcp_f32_e32 v174, v151
	v_add_f32_e32 v151, 1.0, v169
	v_exp_f32_e32 v168, v168
	v_mul_f32_e32 v169, 0xbfb8aa3b, v157
	v_exp_f32_e32 v169, v169
	v_rcp_f32_e32 v176, v151
	v_add_f32_e32 v151, 1.0, v168
	v_rcp_f32_e32 v175, v151
	v_add_f32_e32 v151, 1.0, v169
	v_rcp_f32_e32 v177, v151
	v_pk_mul_f32 v[168:169], v[164:165], v[166:167]
	v_pk_mul_f32 v[170:171], v[158:159], v[170:171]
	v_pk_mul_f32 v[174:175], v[162:163], v[174:175]
	v_pk_mul_f32 v[178:179], v[156:157], v[176:177]

.LBB0_265:
	v_mov_b32_e32 v151, v202
	s_and_b64 vcc, exec, s[6:7]
	s_nop 0
	v_mul_f32_e32 v156, 0x3e0293ee, v151
	v_cndmask_b32_e64 v172, v151, v156, s[56:57]
	v_pk_mul_f32 v[162:163], v[78:79], v[172:173] op_sel_hi:[1,0]
	v_pk_mul_f32 v[164:165], v[76:77], v[172:173] op_sel_hi:[1,0]
	s_waitcnt lgkmcnt(0)
	v_pk_mul_f32 v[156:157], v[74:75], v[172:173] op_sel_hi:[1,0]
	v_pk_mul_f32 v[158:159], v[72:73], v[172:173] op_sel_hi:[1,0]
	v_mov_b32_e32 v168, v164
	v_mov_b32_e32 v169, v165
	v_mov_b32_e32 v174, v162
	v_mov_b32_e32 v175, v163
	v_mov_b32_e32 v170, v158
	v_mov_b32_e32 v171, v159
	v_mov_b32_e32 v178, v156
	v_mov_b32_e32 v179, v157
	s_cbranch_vccnz .LBB0_267
	v_mul_f32_e32 v151, 0xbfb8aa3b, v164
	v_exp_f32_e32 v151, v151
	v_mul_f32_e32 v166, 0xbfb8aa3b, v158
	v_exp_f32_e32 v166, v166
	v_mul_f32_e32 v168, 0xbfb8aa3b, v159
	v_add_f32_e32 v151, 1.0, v151
	v_exp_f32_e32 v168, v168
	v_add_f32_e32 v167, 1.0, v166
	v_rcp_f32_e32 v166, v151
	v_mul_f32_e32 v151, 0xbfb8aa3b, v165
	v_exp_f32_e32 v151, v151
	v_rcp_f32_e32 v170, v167
	v_mul_f32_e32 v169, 0xbfb8aa3b, v156
	v_exp_f32_e32 v169, v169
	v_add_f32_e32 v151, 1.0, v151
	v_rcp_f32_e32 v167, v151
	v_add_f32_e32 v151, 1.0, v168
	v_mul_f32_e32 v168, 0xbfb8aa3b, v162
	v_exp_f32_e32 v168, v168
	v_rcp_f32_e32 v171, v151
	v_add_f32_e32 v151, 1.0, v168
	v_mul_f32_e32 v168, 0xbfb8aa3b, v163
	v_rcp_f32_e32 v174, v151
	v_add_f32_e32 v151, 1.0, v169
	v_exp_f32_e32 v168, v168
	v_mul_f32_e32 v169, 0xbfb8aa3b, v157
	v_exp_f32_e32 v169, v169
	v_rcp_f32_e32 v176, v151
	v_add_f32_e32 v151, 1.0, v168
	v_rcp_f32_e32 v175, v151
	v_add_f32_e32 v151, 1.0, v169
	v_rcp_f32_e32 v177, v151
	v_pk_mul_f32 v[168:169], v[164:165], v[166:167]
	v_pk_mul_f32 v[170:171], v[158:159], v[170:171]
	v_pk_mul_f32 v[174:175], v[162:163], v[174:175]
	v_pk_mul_f32 v[178:179], v[156:157], v[176:177]

.LBB0_273:
	v_mov_b32_e32 v151, v203
	s_and_b64 vcc, exec, s[6:7]
	s_nop 0
	v_mul_f32_e32 v156, 0x3e0293ee, v151
	v_cndmask_b32_e64 v172, v151, v156, s[56:57]
	v_pk_mul_f32 v[162:163], v[62:63], v[172:173] op_sel_hi:[1,0]
	v_pk_mul_f32 v[164:165], v[60:61], v[172:173] op_sel_hi:[1,0]
	s_waitcnt lgkmcnt(0)
	v_pk_mul_f32 v[156:157], v[58:59], v[172:173] op_sel_hi:[1,0]
	v_pk_mul_f32 v[158:159], v[56:57], v[172:173] op_sel_hi:[1,0]
	v_mov_b32_e32 v168, v164
	v_mov_b32_e32 v169, v165
	v_mov_b32_e32 v174, v162
	v_mov_b32_e32 v175, v163
	v_mov_b32_e32 v170, v158
	v_mov_b32_e32 v171, v159
	v_mov_b32_e32 v178, v156
	v_mov_b32_e32 v179, v157
	s_cbranch_vccnz .LBB0_275
	v_mul_f32_e32 v151, 0xbfb8aa3b, v164
	v_exp_f32_e32 v151, v151
	v_mul_f32_e32 v166, 0xbfb8aa3b, v158
	v_exp_f32_e32 v166, v166
	v_mul_f32_e32 v168, 0xbfb8aa3b, v159
	v_add_f32_e32 v151, 1.0, v151
	v_exp_f32_e32 v168, v168
	v_add_f32_e32 v167, 1.0, v166
	v_rcp_f32_e32 v166, v151
	v_mul_f32_e32 v151, 0xbfb8aa3b, v165
	v_exp_f32_e32 v151, v151
	v_rcp_f32_e32 v170, v167
	v_mul_f32_e32 v169, 0xbfb8aa3b, v156
	v_exp_f32_e32 v169, v169
	v_add_f32_e32 v151, 1.0, v151
	v_rcp_f32_e32 v167, v151
	v_add_f32_e32 v151, 1.0, v168
	v_mul_f32_e32 v168, 0xbfb8aa3b, v162
	v_exp_f32_e32 v168, v168
	v_rcp_f32_e32 v171, v151
	v_add_f32_e32 v151, 1.0, v168
	v_mul_f32_e32 v168, 0xbfb8aa3b, v163
	v_rcp_f32_e32 v174, v151
	v_add_f32_e32 v151, 1.0, v169
	v_exp_f32_e32 v168, v168
	v_mul_f32_e32 v169, 0xbfb8aa3b, v157
	v_exp_f32_e32 v169, v169
	v_rcp_f32_e32 v176, v151
	v_add_f32_e32 v151, 1.0, v168
	v_rcp_f32_e32 v175, v151
	v_add_f32_e32 v151, 1.0, v169
	v_rcp_f32_e32 v177, v151
	v_pk_mul_f32 v[168:169], v[164:165], v[166:167]
	v_pk_mul_f32 v[170:171], v[158:159], v[170:171]
	v_pk_mul_f32 v[174:175], v[162:163], v[174:175]
	v_pk_mul_f32 v[178:179], v[156:157], v[176:177]

.LBB0_281:
	v_mov_b32_e32 v151, v204
	s_and_b64 vcc, exec, s[6:7]
	s_nop 0
	v_mul_f32_e32 v156, 0x3e0293ee, v151
	v_cndmask_b32_e64 v172, v151, v156, s[56:57]
	v_pk_mul_f32 v[162:163], v[46:47], v[172:173] op_sel_hi:[1,0]
	v_pk_mul_f32 v[164:165], v[44:45], v[172:173] op_sel_hi:[1,0]
	s_waitcnt lgkmcnt(0)
	v_pk_mul_f32 v[156:157], v[42:43], v[172:173] op_sel_hi:[1,0]
	v_pk_mul_f32 v[158:159], v[40:41], v[172:173] op_sel_hi:[1,0]
	v_mov_b32_e32 v168, v164
	v_mov_b32_e32 v169, v165
	v_mov_b32_e32 v174, v162
	v_mov_b32_e32 v175, v163
	v_mov_b32_e32 v170, v158
	v_mov_b32_e32 v171, v159
	v_mov_b32_e32 v178, v156
	v_mov_b32_e32 v179, v157
	s_cbranch_vccnz .LBB0_283
	v_mul_f32_e32 v151, 0xbfb8aa3b, v164
	v_exp_f32_e32 v151, v151
	v_mul_f32_e32 v166, 0xbfb8aa3b, v158
	v_exp_f32_e32 v166, v166
	v_mul_f32_e32 v168, 0xbfb8aa3b, v159
	v_add_f32_e32 v151, 1.0, v151
	v_exp_f32_e32 v168, v168
	v_add_f32_e32 v167, 1.0, v166
	v_rcp_f32_e32 v166, v151
	v_mul_f32_e32 v151, 0xbfb8aa3b, v165
	v_exp_f32_e32 v151, v151
	v_rcp_f32_e32 v170, v167
	v_mul_f32_e32 v169, 0xbfb8aa3b, v156
	v_exp_f32_e32 v169, v169
	v_add_f32_e32 v151, 1.0, v151
	v_rcp_f32_e32 v167, v151
	v_add_f32_e32 v151, 1.0, v168
	v_mul_f32_e32 v168, 0xbfb8aa3b, v162
	v_exp_f32_e32 v168, v168
	v_rcp_f32_e32 v171, v151
	v_add_f32_e32 v151, 1.0, v168
	v_mul_f32_e32 v168, 0xbfb8aa3b, v163
	v_rcp_f32_e32 v174, v151
	v_add_f32_e32 v151, 1.0, v169
	v_exp_f32_e32 v168, v168
	v_mul_f32_e32 v169, 0xbfb8aa3b, v157
	v_exp_f32_e32 v169, v169
	v_rcp_f32_e32 v176, v151
	v_add_f32_e32 v151, 1.0, v168
	v_rcp_f32_e32 v175, v151
	v_add_f32_e32 v151, 1.0, v169
	v_rcp_f32_e32 v177, v151
	v_pk_mul_f32 v[168:169], v[164:165], v[166:167]
	v_pk_mul_f32 v[170:171], v[158:159], v[170:171]
	v_pk_mul_f32 v[174:175], v[162:163], v[174:175]
	v_pk_mul_f32 v[178:179], v[156:157], v[176:177]

.LBB0_289:
	v_mov_b32_e32 v151, v205
	s_and_b64 vcc, exec, s[6:7]
	s_nop 0
	v_mul_f32_e32 v156, 0x3e0293ee, v151
	v_cndmask_b32_e64 v172, v151, v156, s[56:57]
	v_pk_mul_f32 v[162:163], v[30:31], v[172:173] op_sel_hi:[1,0]
	v_pk_mul_f32 v[164:165], v[28:29], v[172:173] op_sel_hi:[1,0]
	s_waitcnt lgkmcnt(0)
	v_pk_mul_f32 v[156:157], v[26:27], v[172:173] op_sel_hi:[1,0]
	v_pk_mul_f32 v[158:159], v[24:25], v[172:173] op_sel_hi:[1,0]
	v_mov_b32_e32 v168, v164
	v_mov_b32_e32 v169, v165
	v_mov_b32_e32 v174, v162
	v_mov_b32_e32 v175, v163
	v_mov_b32_e32 v170, v158
	v_mov_b32_e32 v171, v159
	v_mov_b32_e32 v178, v156
	v_mov_b32_e32 v179, v157
	s_cbranch_vccnz .LBB0_291
	v_mul_f32_e32 v151, 0xbfb8aa3b, v164
	v_exp_f32_e32 v151, v151
	v_mul_f32_e32 v166, 0xbfb8aa3b, v158
	v_exp_f32_e32 v166, v166
	v_mul_f32_e32 v168, 0xbfb8aa3b, v159
	v_add_f32_e32 v151, 1.0, v151
	v_exp_f32_e32 v168, v168
	v_add_f32_e32 v167, 1.0, v166
	v_rcp_f32_e32 v166, v151
	v_mul_f32_e32 v151, 0xbfb8aa3b, v165
	v_exp_f32_e32 v151, v151
	v_rcp_f32_e32 v170, v167
	v_mul_f32_e32 v169, 0xbfb8aa3b, v156
	v_exp_f32_e32 v169, v169
	v_add_f32_e32 v151, 1.0, v151
	v_rcp_f32_e32 v167, v151
	v_add_f32_e32 v151, 1.0, v168
	v_mul_f32_e32 v168, 0xbfb8aa3b, v162
	v_exp_f32_e32 v168, v168
	v_rcp_f32_e32 v171, v151
	v_add_f32_e32 v151, 1.0, v168
	v_mul_f32_e32 v168, 0xbfb8aa3b, v163
	v_rcp_f32_e32 v174, v151
	v_add_f32_e32 v151, 1.0, v169
	v_exp_f32_e32 v168, v168
	v_mul_f32_e32 v169, 0xbfb8aa3b, v157
	v_exp_f32_e32 v169, v169
	v_rcp_f32_e32 v176, v151
	v_add_f32_e32 v151, 1.0, v168
	v_rcp_f32_e32 v175, v151
	v_add_f32_e32 v151, 1.0, v169
	v_rcp_f32_e32 v177, v151
	v_pk_mul_f32 v[168:169], v[164:165], v[166:167]
	v_pk_mul_f32 v[170:171], v[158:159], v[170:171]
	v_pk_mul_f32 v[174:175], v[162:163], v[174:175]
	v_pk_mul_f32 v[178:179], v[156:157], v[176:177]

.LBB0_297:
	v_mov_b32_e32 v151, v206
	s_and_b64 vcc, exec, s[6:7]
	s_nop 0
	v_mul_f32_e32 v154, 0x3e0293ee, v151
	v_cndmask_b32_e64 v168, v151, v154, s[56:57]
	v_pk_mul_f32 v[158:159], v[14:15], v[168:169] op_sel_hi:[1,0]
	v_pk_mul_f32 v[162:163], v[12:13], v[168:169] op_sel_hi:[1,0]
	v_pk_mul_f32 v[154:155], v[10:11], v[168:169] op_sel_hi:[1,0]
	s_waitcnt lgkmcnt(0)
	v_pk_mul_f32 v[156:157], v[8:9], v[168:169] op_sel_hi:[1,0]
	v_mov_b32_e32 v166, v162
	v_mov_b32_e32 v167, v163
	v_mov_b32_e32 v174, v158
	v_mov_b32_e32 v175, v159
	v_mov_b32_e32 v170, v156
	v_mov_b32_e32 v171, v157
	v_mov_b32_e32 v176, v154
	v_mov_b32_e32 v177, v155
	s_cbranch_vccnz .LBB0_299
	v_mul_f32_e32 v151, 0xbfb8aa3b, v162
	v_exp_f32_e32 v151, v151
	v_mul_f32_e32 v164, 0xbfb8aa3b, v156
	v_exp_f32_e32 v164, v164
	v_mul_f32_e32 v166, 0xbfb8aa3b, v157
	v_add_f32_e32 v151, 1.0, v151
	v_exp_f32_e32 v166, v166
	v_add_f32_e32 v165, 1.0, v164
	v_rcp_f32_e32 v164, v151
	v_mul_f32_e32 v151, 0xbfb8aa3b, v163
	v_exp_f32_e32 v151, v151
	v_rcp_f32_e32 v170, v165
	v_mul_f32_e32 v167, 0xbfb8aa3b, v154
	v_exp_f32_e32 v167, v167
	v_add_f32_e32 v151, 1.0, v151
	v_rcp_f32_e32 v165, v151
	v_add_f32_e32 v151, 1.0, v166
	v_mul_f32_e32 v166, 0xbfb8aa3b, v158
	v_exp_f32_e32 v166, v166
	v_rcp_f32_e32 v171, v151
	v_add_f32_e32 v151, 1.0, v166
	v_mul_f32_e32 v166, 0xbfb8aa3b, v159
	v_rcp_f32_e32 v172, v151
	v_add_f32_e32 v151, 1.0, v167
	v_exp_f32_e32 v166, v166
	v_mul_f32_e32 v167, 0xbfb8aa3b, v155
	v_exp_f32_e32 v167, v167
	v_rcp_f32_e32 v176, v151
	v_add_f32_e32 v151, 1.0, v166
	v_rcp_f32_e32 v173, v151
	v_add_f32_e32 v151, 1.0, v167
	v_rcp_f32_e32 v177, v151
	v_pk_mul_f32 v[166:167], v[162:163], v[164:165]
	v_pk_mul_f32 v[170:171], v[156:157], v[170:171]
	v_pk_mul_f32 v[174:175], v[158:159], v[172:173]
	v_pk_mul_f32 v[176:177], v[154:155], v[176:177]

.Lscan_entry:
	s_mov_b32 s0, 0
	s_cmpk_ge_i32 s76, 32
	v_mov_b32_e32 v10, v160
	v_mov_b32_e32 v0, v161
	s_cbranch_scc1 .LBB0_458
	s_sub_i32 s0, s76, s0
	s_lshr_b32 s2, s0, 3
	s_mov_b32 s3, 0
	s_lshl_b64 s[2:3], s[2:3], 17
	s_add_u32 s1, s30, s2
	s_addc_u32 s3, s31, s3
	s_and_b32 s2, s0, 7
	s_lshl_b32 s4, s2, 2
	v_mov_b32_e32 v1, s4
	global_load_dword v6, v1, s[84:85]
	v_lshlrev_b32_e32 v0, 3, v0
	s_add_u32 s2, s1, s4
	v_ashrrev_i32_e32 v1, 31, v0
	s_addc_u32 s3, s3, 0
	v_lshlrev_b64 v[2:3], 5, v[0:1]
	v_lshl_add_u64 v[2:3], s[2:3], 0, v[2:3]
	global_load_dword v7, v[2:3], off
	global_load_dword v8, v[2:3], off offset:32
	global_load_dword v9, v[2:3], off offset:64
	global_load_dword v11, v[2:3], off offset:96
	global_load_dword v12, v[2:3], off offset:128
	global_load_dword v13, v[2:3], off offset:160
	global_load_dword v14, v[2:3], off offset:192
	s_nop 0
	global_load_dword v2, v[2:3], off offset:224
	s_mov_b32 s4, 0xbfb8aa3b
	s_mov_b32 s7, 0xb2a5705f
	s_mov_b32 s3, 0x42ce8ed0
	s_mov_b32 s5, 0xc2b17218
	v_mov_b32_e32 v3, 0x7f800000
	s_mov_b32 s6, 0x3f2aaaab
	s_mov_b32 s2, 0x3f317218
	v_mov_b32_e32 v5, 0x3ecc95a3
	s_mov_b32 s1, 0x7f800000
	s_mov_b32 s8, 0x33800000
	v_mov_b32_e32 v4, 0x3f2aaada
	s_waitcnt vmcnt(0)
	v_add_f32_e32 v15, v6, v7
	v_mul_f32_e64 v7, |v15|, s4
	v_add_f32_e32 v16, v6, v9
	v_add_f32_e32 v17, v6, v11
	v_fma_f32 v11, |v15|, s4, -v7
	v_add_f32_e32 v9, v6, v13
	v_rndne_f32_e32 v13, v7
	v_fma_f32 v11, |v15|, s7, v11
	v_sub_f32_e32 v7, v7, v13
	v_add_f32_e32 v7, v7, v11
	v_cvt_i32_f32_e32 v13, v13
	v_exp_f32_e32 v11, v7
	v_cmp_ngt_f32_e64 vcc, |v15|, s3
	v_add_f32_e32 v8, v6, v8
	v_add_f32_e32 v12, v6, v12
	v_ldexp_f32 v11, v11, v13
	v_cndmask_b32_e32 v11, 0, v11, vcc
	v_cmp_nlt_f32_e64 vcc, |v15|, s5
	v_add_f32_e32 v7, v6, v14
	v_add_f32_e32 v6, v6, v2
	v_cndmask_b32_e32 v11, v3, v11, vcc
	v_add_f32_e32 v13, 1.0, v11
	v_min_f32_e32 v2, 0, v15
	v_add_f32_e32 v18, -1.0, v13
	v_frexp_mant_f32_e32 v19, v13
	v_cvt_f64_f32_e32 v[14:15], v13
	v_sub_f32_e32 v20, v18, v13
	v_frexp_exp_i32_f64_e32 v14, v[14:15]
	v_cmp_gt_f32_e32 vcc, s6, v19
	v_sub_f32_e32 v18, v11, v18
	v_add_f32_e32 v15, 1.0, v20
	v_subbrev_co_u32_e32 v14, vcc, 0, v14, vcc
	v_add_f32_e32 v15, v18, v15
	v_sub_u32_e32 v18, 0, v14
	v_cvt_f32_i32_e32 v14, v14
	v_ldexp_f32 v13, v13, v18
	v_ldexp_f32 v15, v15, v18
	v_add_f32_e32 v18, -1.0, v13
	v_add_f32_e32 v19, 1.0, v13
	v_add_f32_e32 v20, 1.0, v18
	v_add_f32_e32 v21, -1.0, v19
	v_sub_f32_e32 v20, v13, v20
	v_sub_f32_e32 v13, v13, v21
	v_mul_f32_e32 v21, 0x3f317218, v14
	v_add_f32_e32 v20, v15, v20
	v_add_f32_e32 v13, v15, v13
	v_fma_f32 v15, v14, s2, -v21
	v_add_f32_e32 v22, v18, v20
	v_add_f32_e32 v23, v19, v13
	v_fmac_f32_e32 v15, 0xb102e308, v14
	v_sub_f32_e32 v14, v18, v22
	v_sub_f32_e32 v18, v19, v23
	v_rcp_f32_e32 v19, v23
	v_add_f32_e32 v24, v21, v15
	v_add_f32_e32 v13, v13, v18
	v_sub_f32_e32 v18, v24, v21
	v_sub_f32_e32 v15, v15, v18
	v_mul_f32_e32 v18, v22, v19
	v_add_f32_e32 v14, v20, v14
	v_mul_f32_e32 v20, v23, v18
	v_fma_f32 v21, v18, v23, -v20
	v_fmac_f32_e32 v21, v18, v13
	v_add_f32_e32 v25, v20, v21
	v_sub_f32_e32 v26, v22, v25
	v_sub_f32_e32 v20, v25, v20
	v_sub_f32_e32 v22, v22, v26
	v_sub_f32_e32 v20, v20, v21
	v_sub_f32_e32 v21, v22, v25
	v_add_f32_e32 v14, v14, v21
	v_add_f32_e32 v14, v20, v14
	v_add_f32_e32 v20, v26, v14
	v_mul_f32_e32 v21, v19, v20
	v_sub_f32_e32 v22, v26, v20
	v_mul_f32_e32 v25, v23, v21
	v_add_f32_e32 v14, v14, v22
	v_add_f32_e32 v22, v18, v21
	v_fma_f32 v23, v21, v23, -v25
	v_sub_f32_e32 v18, v22, v18
	v_fmac_f32_e32 v23, v21, v13
	v_sub_f32_e32 v13, v21, v18
	v_add_f32_e32 v18, v25, v23
	v_sub_f32_e32 v21, v18, v25
	v_sub_f32_e32 v25, v20, v18
	v_sub_f32_e32 v20, v20, v25
	v_sub_f32_e32 v18, v20, v18
	v_sub_f32_e32 v21, v21, v23
	v_add_f32_e32 v14, v14, v18
	v_add_f32_e32 v14, v21, v14
	v_add_f32_e32 v14, v25, v14
	v_mul_f32_e32 v14, v19, v14
	v_add_f32_e32 v13, v13, v14
	v_add_f32_e32 v14, v22, v13
	v_mul_f32_e32 v18, v14, v14
	v_fmamk_f32 v21, v18, 0x3e9b6dac, v5
	v_sub_f32_e32 v19, v14, v22
	v_ldexp_f32 v20, v14, 1
	v_mul_f32_e32 v14, v14, v18
	v_fmaak_f32 v18, v18, v21, 0x3f2aaada
	v_mul_f32_e32 v14, v14, v18
	v_add_f32_e32 v18, v20, v14
	v_sub_f32_e32 v13, v13, v19
	v_sub_f32_e32 v19, v18, v20
	v_ldexp_f32 v13, v13, 1
	v_sub_f32_e32 v14, v14, v19
	v_add_f32_e32 v13, v13, v14
	v_add_f32_e32 v14, v18, v13
	v_sub_f32_e32 v18, v14, v18
	v_add_f32_e32 v19, v24, v14
	v_sub_f32_e32 v13, v13, v18
	v_sub_f32_e32 v18, v19, v24
	v_sub_f32_e32 v20, v19, v18
	v_sub_f32_e32 v14, v14, v18
	v_add_f32_e32 v18, v15, v13
	v_sub_f32_e32 v20, v24, v20
	v_sub_f32_e32 v21, v18, v15
	v_add_f32_e32 v14, v14, v20
	v_sub_f32_e32 v20, v18, v21
	v_sub_f32_e32 v13, v13, v21
	v_sub_f32_e32 v15, v15, v20
	v_add_f32_e32 v14, v18, v14
	v_add_f32_e32 v13, v13, v15
	v_add_f32_e32 v15, v19, v14
	v_sub_f32_e32 v18, v15, v19
	v_sub_f32_e32 v14, v14, v18
	v_add_f32_e32 v13, v13, v14
	v_mul_f32_e64 v14, |v8|, s4
	v_add_f32_e32 v13, v15, v13
	v_fma_f32 v15, |v8|, s4, -v14
	v_rndne_f32_e32 v18, v14
	v_fma_f32 v15, |v8|, s7, v15
	v_sub_f32_e32 v14, v14, v18
	v_add_f32_e32 v14, v14, v15
	v_exp_f32_e32 v14, v14
	v_cvt_i32_f32_e32 v15, v18
	v_cmp_neq_f32_e32 vcc, s1, v11
	s_nop 1
	v_cndmask_b32_e32 v13, v3, v13, vcc
	v_cmp_lt_f32_e64 vcc, |v11|, s8
	s_nop 1
	v_cndmask_b32_e32 v11, v13, v11, vcc
	v_ldexp_f32 v13, v14, v15
	v_cmp_ngt_f32_e64 vcc, |v8|, s3
	v_sub_f32_e32 v2, v2, v11
	v_min_f32_e32 v11, 0, v8
	v_cndmask_b32_e32 v13, 0, v13, vcc
	v_cmp_nlt_f32_e64 vcc, |v8|, s5
	s_nop 1
	v_cndmask_b32_e32 v8, v3, v13, vcc
	v_add_f32_e32 v13, 1.0, v8
	v_add_f32_e32 v14, -1.0, v13
	v_sub_f32_e32 v15, v14, v13
	v_add_f32_e32 v15, 1.0, v15
	v_sub_f32_e32 v14, v8, v14
	v_add_f32_e32 v18, v14, v15
	v_frexp_mant_f32_e32 v19, v13
	v_cvt_f64_f32_e32 v[14:15], v13
	v_frexp_exp_i32_f64_e32 v14, v[14:15]
	v_cmp_gt_f32_e32 vcc, s6, v19
	s_nop 1
	v_subbrev_co_u32_e32 v14, vcc, 0, v14, vcc
	v_sub_u32_e32 v15, 0, v14
	v_ldexp_f32 v13, v13, v15
	v_ldexp_f32 v15, v18, v15
	v_add_f32_e32 v18, -1.0, v13
	v_add_f32_e32 v21, 1.0, v13
	v_add_f32_e32 v19, 1.0, v18
	v_add_f32_e32 v22, -1.0, v21
	v_sub_f32_e32 v19, v13, v19
	v_sub_f32_e32 v13, v13, v22
	v_add_f32_e32 v13, v15, v13
	v_add_f32_e32 v19, v15, v19
	v_add_f32_e32 v15, v21, v13
	v_rcp_f32_e32 v22, v15
	v_add_f32_e32 v20, v18, v19
	v_sub_f32_e32 v18, v18, v20
	v_add_f32_e32 v18, v19, v18
	v_sub_f32_e32 v19, v21, v15
	v_add_f32_e32 v13, v13, v19
	v_mul_f32_e32 v19, v20, v22
	v_mul_f32_e32 v21, v15, v19
	v_fma_f32 v23, v19, v15, -v21
	v_fmac_f32_e32 v23, v19, v13
	v_add_f32_e32 v24, v21, v23
	v_sub_f32_e32 v25, v20, v24
	v_sub_f32_e32 v20, v20, v25
	v_sub_f32_e32 v21, v24, v21
	v_sub_f32_e32 v20, v20, v24
	v_add_f32_e32 v18, v18, v20
	v_sub_f32_e32 v20, v21, v23
	v_add_f32_e32 v18, v20, v18
	v_add_f32_e32 v20, v25, v18
	v_mul_f32_e32 v21, v22, v20
	v_mul_f32_e32 v23, v15, v21
	v_fma_f32 v15, v21, v15, -v23
	v_fmac_f32_e32 v15, v21, v13
	v_sub_f32_e32 v13, v25, v20
	v_add_f32_e32 v13, v18, v13
	v_add_f32_e32 v18, v23, v15
	v_sub_f32_e32 v24, v20, v18
	v_sub_f32_e32 v20, v20, v24
	v_sub_f32_e32 v23, v18, v23
	v_sub_f32_e32 v18, v20, v18
	v_add_f32_e32 v13, v13, v18
	v_sub_f32_e32 v15, v23, v15
	v_cvt_f32_i32_e32 v14, v14
	v_add_f32_e32 v13, v15, v13
	v_add_f32_e32 v15, v19, v21
	v_add_f32_e32 v13, v24, v13
	v_sub_f32_e32 v18, v15, v19
	v_mul_f32_e32 v13, v22, v13
	v_sub_f32_e32 v18, v21, v18
	v_add_f32_e32 v13, v18, v13
	v_mul_f32_e32 v21, 0x3f317218, v14
	v_add_f32_e32 v18, v15, v13
	v_fma_f32 v22, v14, s2, -v21
	v_mul_f32_e32 v19, v18, v18
	v_fmac_f32_e32 v22, 0xb102e308, v14
	v_sub_f32_e32 v14, v18, v15
	v_fmamk_f32 v20, v19, 0x3e9b6dac, v5
	v_sub_f32_e32 v13, v13, v14
	v_add_f32_e32 v14, v21, v22
	v_fmaak_f32 v20, v19, v20, 0x3f2aaada
	v_sub_f32_e32 v15, v14, v21
	v_ldexp_f32 v21, v18, 1
	v_mul_f32_e32 v18, v18, v19
	v_mul_f32_e32 v18, v18, v20
	v_add_f32_e32 v19, v21, v18
	v_sub_f32_e32 v20, v19, v21
	v_ldexp_f32 v13, v13, 1
	v_sub_f32_e32 v18, v18, v20
	v_add_f32_e32 v13, v13, v18
	v_add_f32_e32 v18, v19, v13
	v_sub_f32_e32 v19, v18, v19
	v_sub_f32_e32 v13, v13, v19
	v_add_f32_e32 v19, v14, v18
	v_sub_f32_e32 v20, v19, v14
	v_sub_f32_e32 v21, v19, v20
	v_sub_f32_e32 v15, v22, v15
	v_sub_f32_e32 v14, v14, v21
	v_sub_f32_e32 v18, v18, v20
	v_add_f32_e32 v14, v18, v14
	v_add_f32_e32 v18, v15, v13
	v_sub_f32_e32 v20, v18, v15
	v_sub_f32_e32 v21, v18, v20
	v_sub_f32_e32 v15, v15, v21
	v_sub_f32_e32 v13, v13, v20
	v_add_f32_e32 v14, v18, v14
	v_add_f32_e32 v13, v13, v15
	v_add_f32_e32 v15, v19, v14
	v_sub_f32_e32 v18, v15, v19
	v_sub_f32_e32 v14, v14, v18
	v_add_f32_e32 v13, v13, v14
	v_mul_f32_e64 v14, |v16|, s4
	v_add_f32_e32 v13, v15, v13
	v_fma_f32 v15, |v16|, s4, -v14
	v_rndne_f32_e32 v18, v14
	v_fma_f32 v15, |v16|, s7, v15
	v_sub_f32_e32 v14, v14, v18
	v_add_f32_e32 v14, v14, v15
	v_exp_f32_e32 v14, v14
	v_cvt_i32_f32_e32 v15, v18
	v_cmp_neq_f32_e32 vcc, s1, v8
	s_nop 1
	v_cndmask_b32_e32 v13, v3, v13, vcc
	v_cmp_lt_f32_e64 vcc, |v8|, s8
	s_nop 1
	v_cndmask_b32_e32 v8, v13, v8, vcc
	v_ldexp_f32 v13, v14, v15
	v_cmp_ngt_f32_e64 vcc, |v16|, s3
	v_sub_f32_e32 v8, v11, v8
	v_min_f32_e32 v11, 0, v16
	v_cndmask_b32_e32 v13, 0, v13, vcc
	v_cmp_nlt_f32_e64 vcc, |v16|, s5
	s_nop 1
	v_cndmask_b32_e32 v13, v3, v13, vcc
	v_add_f32_e32 v16, 1.0, v13
	v_add_f32_e32 v14, -1.0, v16
	v_sub_f32_e32 v15, v14, v16
	v_add_f32_e32 v15, 1.0, v15
	v_sub_f32_e32 v14, v13, v14
	v_add_f32_e32 v18, v14, v15
	v_frexp_mant_f32_e32 v19, v16
	v_cvt_f64_f32_e32 v[14:15], v16
	v_frexp_exp_i32_f64_e32 v14, v[14:15]
	v_cmp_gt_f32_e32 vcc, s6, v19
	s_nop 1
	v_subbrev_co_u32_e32 v14, vcc, 0, v14, vcc
	v_sub_u32_e32 v15, 0, v14
	v_ldexp_f32 v16, v16, v15
	v_ldexp_f32 v15, v18, v15
	v_add_f32_e32 v18, -1.0, v16
	v_add_f32_e32 v21, 1.0, v16
	v_add_f32_e32 v19, 1.0, v18
	v_add_f32_e32 v22, -1.0, v21
	v_sub_f32_e32 v19, v16, v19
	v_sub_f32_e32 v16, v16, v22
	v_add_f32_e32 v19, v15, v19
	v_add_f32_e32 v15, v15, v16
	v_add_f32_e32 v16, v21, v15
	v_rcp_f32_e32 v22, v16
	v_add_f32_e32 v20, v18, v19
	v_sub_f32_e32 v18, v18, v20
	v_add_f32_e32 v18, v19, v18
	v_sub_f32_e32 v19, v21, v16
	v_add_f32_e32 v15, v15, v19
	v_mul_f32_e32 v19, v20, v22
	v_mul_f32_e32 v21, v16, v19
	v_fma_f32 v23, v19, v16, -v21
	v_fmac_f32_e32 v23, v19, v15
	v_add_f32_e32 v24, v21, v23
	v_sub_f32_e32 v25, v20, v24
	v_sub_f32_e32 v20, v20, v25
	v_sub_f32_e32 v21, v24, v21
	v_sub_f32_e32 v20, v20, v24
	v_add_f32_e32 v18, v18, v20
	v_sub_f32_e32 v20, v21, v23
	v_add_f32_e32 v18, v20, v18
	v_add_f32_e32 v20, v25, v18
	v_mul_f32_e32 v21, v22, v20
	v_mul_f32_e32 v23, v16, v21
	v_fma_f32 v16, v21, v16, -v23
	v_fmac_f32_e32 v16, v21, v15
	v_sub_f32_e32 v15, v25, v20
	v_add_f32_e32 v15, v18, v15
	v_add_f32_e32 v18, v23, v16
	v_sub_f32_e32 v24, v20, v18
	v_sub_f32_e32 v20, v20, v24
	v_sub_f32_e32 v23, v18, v23
	v_sub_f32_e32 v18, v20, v18
	v_add_f32_e32 v15, v15, v18
	v_sub_f32_e32 v16, v23, v16
	v_cvt_f32_i32_e32 v14, v14
	v_add_f32_e32 v15, v16, v15
	v_add_f32_e32 v16, v19, v21
	v_add_f32_e32 v15, v24, v15
	v_sub_f32_e32 v18, v16, v19
	v_mul_f32_e32 v15, v22, v15
	v_sub_f32_e32 v18, v21, v18
	v_add_f32_e32 v15, v18, v15
	v_mul_f32_e32 v21, 0x3f317218, v14
	v_add_f32_e32 v18, v16, v15
	v_fma_f32 v22, v14, s2, -v21
	v_mul_f32_e32 v19, v18, v18
	v_fmac_f32_e32 v22, 0xb102e308, v14
	v_sub_f32_e32 v14, v18, v16
	v_fmamk_f32 v20, v19, 0x3e9b6dac, v5
	v_sub_f32_e32 v14, v15, v14
	v_add_f32_e32 v15, v21, v22
	v_fmaak_f32 v20, v19, v20, 0x3f2aaada
	v_sub_f32_e32 v16, v15, v21
	v_ldexp_f32 v21, v18, 1
	v_mul_f32_e32 v18, v18, v19
	v_mul_f32_e32 v18, v18, v20
	v_add_f32_e32 v19, v21, v18
	v_sub_f32_e32 v20, v19, v21
	v_ldexp_f32 v14, v14, 1
	v_sub_f32_e32 v18, v18, v20
	v_add_f32_e32 v14, v14, v18
	v_add_f32_e32 v18, v19, v14
	v_sub_f32_e32 v19, v18, v19
	v_sub_f32_e32 v14, v14, v19
	v_add_f32_e32 v19, v15, v18
	v_sub_f32_e32 v20, v19, v15
	v_sub_f32_e32 v21, v19, v20
	v_sub_f32_e32 v16, v22, v16
	v_sub_f32_e32 v15, v15, v21
	v_sub_f32_e32 v18, v18, v20
	v_add_f32_e32 v15, v18, v15
	v_add_f32_e32 v18, v16, v14
	v_sub_f32_e32 v20, v18, v16
	v_sub_f32_e32 v21, v18, v20
	v_sub_f32_e32 v16, v16, v21
	v_sub_f32_e32 v14, v14, v20
	v_add_f32_e32 v15, v18, v15
	v_add_f32_e32 v14, v14, v16
	v_add_f32_e32 v16, v19, v15
	v_sub_f32_e32 v18, v16, v19
	v_sub_f32_e32 v15, v15, v18
	v_add_f32_e32 v14, v14, v15
	v_mul_f32_e64 v15, |v17|, s4
	v_add_f32_e32 v14, v16, v14
	v_fma_f32 v16, |v17|, s4, -v15
	v_rndne_f32_e32 v18, v15
	v_fma_f32 v16, |v17|, s7, v16
	v_sub_f32_e32 v15, v15, v18
	v_add_f32_e32 v15, v15, v16
	v_exp_f32_e32 v15, v15
	v_cvt_i32_f32_e32 v16, v18
	v_cmp_neq_f32_e32 vcc, s1, v13
	s_nop 1
	v_cndmask_b32_e32 v14, v3, v14, vcc
	v_cmp_lt_f32_e64 vcc, |v13|, s8
	s_nop 1
	v_cndmask_b32_e32 v13, v14, v13, vcc
	v_ldexp_f32 v14, v15, v16
	v_cmp_ngt_f32_e64 vcc, |v17|, s3
	v_sub_f32_e32 v11, v11, v13
	v_min_f32_e32 v13, 0, v17
	v_cndmask_b32_e32 v14, 0, v14, vcc
	v_cmp_nlt_f32_e64 vcc, |v17|, s5
	s_nop 1
	v_cndmask_b32_e32 v16, v3, v14, vcc
	v_add_f32_e32 v17, 1.0, v16
	v_add_f32_e32 v14, -1.0, v17
	v_sub_f32_e32 v15, v14, v17
	v_add_f32_e32 v15, 1.0, v15
	v_sub_f32_e32 v14, v16, v14
	v_add_f32_e32 v18, v14, v15
	v_frexp_mant_f32_e32 v19, v17
	v_cvt_f64_f32_e32 v[14:15], v17
	v_frexp_exp_i32_f64_e32 v14, v[14:15]
	v_cmp_gt_f32_e32 vcc, s6, v19
	s_nop 1
	v_subbrev_co_u32_e32 v14, vcc, 0, v14, vcc
	v_sub_u32_e32 v15, 0, v14
	v_ldexp_f32 v17, v17, v15
	v_ldexp_f32 v15, v18, v15
	v_add_f32_e32 v18, -1.0, v17
	v_add_f32_e32 v21, 1.0, v17
	v_add_f32_e32 v19, 1.0, v18
	v_add_f32_e32 v22, -1.0, v21
	v_sub_f32_e32 v19, v17, v19
	v_sub_f32_e32 v17, v17, v22
	v_add_f32_e32 v19, v15, v19
	v_add_f32_e32 v15, v15, v17
	v_add_f32_e32 v17, v21, v15
	v_rcp_f32_e32 v22, v17
	v_add_f32_e32 v20, v18, v19
	v_sub_f32_e32 v18, v18, v20
	v_add_f32_e32 v18, v19, v18
	v_sub_f32_e32 v19, v21, v17
	v_add_f32_e32 v15, v15, v19
	v_mul_f32_e32 v19, v20, v22
	v_mul_f32_e32 v21, v17, v19
	v_fma_f32 v23, v19, v17, -v21
	v_fmac_f32_e32 v23, v19, v15
	v_add_f32_e32 v24, v21, v23
	v_sub_f32_e32 v25, v20, v24
	v_sub_f32_e32 v20, v20, v25
	v_sub_f32_e32 v21, v24, v21
	v_sub_f32_e32 v20, v20, v24
	v_add_f32_e32 v18, v18, v20
	v_sub_f32_e32 v20, v21, v23
	v_add_f32_e32 v18, v20, v18
	v_add_f32_e32 v20, v25, v18
	v_mul_f32_e32 v21, v22, v20
	v_mul_f32_e32 v23, v17, v21
	v_fma_f32 v17, v21, v17, -v23
	v_fmac_f32_e32 v17, v21, v15
	v_sub_f32_e32 v15, v25, v20
	v_add_f32_e32 v15, v18, v15
	v_add_f32_e32 v18, v23, v17
	v_sub_f32_e32 v24, v20, v18
	v_sub_f32_e32 v20, v20, v24
	v_sub_f32_e32 v23, v18, v23
	v_sub_f32_e32 v18, v20, v18
	v_add_f32_e32 v15, v15, v18
	v_sub_f32_e32 v17, v23, v17
	v_cvt_f32_i32_e32 v14, v14
	v_add_f32_e32 v15, v17, v15
	v_add_f32_e32 v17, v19, v21
	v_add_f32_e32 v15, v24, v15
	v_sub_f32_e32 v18, v17, v19
	v_mul_f32_e32 v15, v22, v15
	v_sub_f32_e32 v18, v21, v18
	v_add_f32_e32 v15, v18, v15
	v_mul_f32_e32 v21, 0x3f317218, v14
	v_add_f32_e32 v18, v17, v15
	v_fma_f32 v22, v14, s2, -v21
	v_mul_f32_e32 v19, v18, v18
	v_fmac_f32_e32 v22, 0xb102e308, v14
	v_sub_f32_e32 v14, v18, v17
	v_fmamk_f32 v20, v19, 0x3e9b6dac, v5
	v_sub_f32_e32 v14, v15, v14
	v_add_f32_e32 v15, v21, v22
	v_fmaak_f32 v20, v19, v20, 0x3f2aaada
	v_sub_f32_e32 v17, v15, v21
	v_ldexp_f32 v21, v18, 1
	v_mul_f32_e32 v18, v18, v19
	v_mul_f32_e32 v18, v18, v20
	v_add_f32_e32 v19, v21, v18
	v_sub_f32_e32 v20, v19, v21
	v_ldexp_f32 v14, v14, 1
	v_sub_f32_e32 v18, v18, v20
	v_add_f32_e32 v14, v14, v18
	v_add_f32_e32 v18, v19, v14
	v_sub_f32_e32 v19, v18, v19
	v_sub_f32_e32 v14, v14, v19
	v_add_f32_e32 v19, v15, v18
	v_sub_f32_e32 v20, v19, v15
	v_sub_f32_e32 v21, v19, v20
	v_sub_f32_e32 v17, v22, v17
	v_sub_f32_e32 v15, v15, v21
	v_sub_f32_e32 v18, v18, v20
	v_add_f32_e32 v15, v18, v15
	v_add_f32_e32 v18, v17, v14
	v_sub_f32_e32 v20, v18, v17
	v_sub_f32_e32 v21, v18, v20
	v_sub_f32_e32 v17, v17, v21
	v_sub_f32_e32 v14, v14, v20
	v_add_f32_e32 v15, v18, v15
	v_add_f32_e32 v14, v14, v17
	v_add_f32_e32 v17, v19, v15
	v_sub_f32_e32 v18, v17, v19
	v_sub_f32_e32 v15, v15, v18
	v_add_f32_e32 v14, v14, v15
	v_mul_f32_e64 v15, |v12|, s4
	v_add_f32_e32 v14, v17, v14
	v_fma_f32 v17, |v12|, s4, -v15
	v_rndne_f32_e32 v18, v15
	v_fma_f32 v17, |v12|, s7, v17
	v_sub_f32_e32 v15, v15, v18
	v_add_f32_e32 v15, v15, v17
	v_exp_f32_e32 v15, v15
	v_cvt_i32_f32_e32 v17, v18
	v_cmp_neq_f32_e32 vcc, s1, v16
	s_nop 1
	v_cndmask_b32_e32 v14, v3, v14, vcc
	v_cmp_lt_f32_e64 vcc, |v16|, s8
	s_nop 1
	v_cndmask_b32_e32 v14, v14, v16, vcc
	v_sub_f32_e32 v13, v13, v14
	v_ldexp_f32 v14, v15, v17
	v_cmp_ngt_f32_e64 vcc, |v12|, s3
	v_min_f32_e32 v16, 0, v12
	s_nop 0
	v_cndmask_b32_e32 v14, 0, v14, vcc
	v_cmp_nlt_f32_e64 vcc, |v12|, s5
	s_nop 1
	v_cndmask_b32_e32 v12, v3, v14, vcc
	v_add_f32_e32 v17, 1.0, v12
	v_add_f32_e32 v14, -1.0, v17
	v_sub_f32_e32 v15, v14, v17
	v_add_f32_e32 v15, 1.0, v15
	v_sub_f32_e32 v14, v12, v14
	v_add_f32_e32 v18, v14, v15
	v_frexp_mant_f32_e32 v19, v17
	v_cvt_f64_f32_e32 v[14:15], v17
	v_frexp_exp_i32_f64_e32 v14, v[14:15]
	v_cmp_gt_f32_e32 vcc, s6, v19
	s_nop 1
	v_subbrev_co_u32_e32 v14, vcc, 0, v14, vcc
	v_sub_u32_e32 v15, 0, v14
	v_ldexp_f32 v17, v17, v15
	v_ldexp_f32 v15, v18, v15
	v_add_f32_e32 v18, -1.0, v17
	v_add_f32_e32 v21, 1.0, v17
	v_add_f32_e32 v19, 1.0, v18
	v_add_f32_e32 v22, -1.0, v21
	v_sub_f32_e32 v19, v17, v19
	v_sub_f32_e32 v17, v17, v22
	v_add_f32_e32 v19, v15, v19
	v_add_f32_e32 v15, v15, v17
	v_add_f32_e32 v17, v21, v15
	v_rcp_f32_e32 v22, v17
	v_add_f32_e32 v20, v18, v19
	v_sub_f32_e32 v18, v18, v20
	v_add_f32_e32 v18, v19, v18
	v_sub_f32_e32 v19, v21, v17
	v_add_f32_e32 v15, v15, v19
	v_mul_f32_e32 v19, v20, v22
	v_mul_f32_e32 v21, v17, v19
	v_fma_f32 v23, v19, v17, -v21
	v_fmac_f32_e32 v23, v19, v15
	v_add_f32_e32 v24, v21, v23
	v_sub_f32_e32 v25, v20, v24
	v_sub_f32_e32 v20, v20, v25
	v_sub_f32_e32 v21, v24, v21
	v_sub_f32_e32 v20, v20, v24
	v_add_f32_e32 v18, v18, v20
	v_sub_f32_e32 v20, v21, v23
	v_add_f32_e32 v18, v20, v18
	v_add_f32_e32 v20, v25, v18
	v_mul_f32_e32 v21, v22, v20
	v_mul_f32_e32 v23, v17, v21
	v_fma_f32 v17, v21, v17, -v23
	v_fmac_f32_e32 v17, v21, v15
	v_sub_f32_e32 v15, v25, v20
	v_add_f32_e32 v15, v18, v15
	v_add_f32_e32 v18, v23, v17
	v_sub_f32_e32 v24, v20, v18
	v_sub_f32_e32 v20, v20, v24
	v_sub_f32_e32 v23, v18, v23
	v_sub_f32_e32 v18, v20, v18
	v_add_f32_e32 v15, v15, v18
	v_sub_f32_e32 v17, v23, v17
	v_cvt_f32_i32_e32 v14, v14
	v_add_f32_e32 v15, v17, v15
	v_add_f32_e32 v17, v19, v21
	v_add_f32_e32 v15, v24, v15
	v_sub_f32_e32 v18, v17, v19
	v_mul_f32_e32 v15, v22, v15
	v_sub_f32_e32 v18, v21, v18
	v_add_f32_e32 v15, v18, v15
	v_mul_f32_e32 v21, 0x3f317218, v14
	v_add_f32_e32 v18, v17, v15
	v_fma_f32 v22, v14, s2, -v21
	v_mul_f32_e32 v19, v18, v18
	v_fmac_f32_e32 v22, 0xb102e308, v14
	v_sub_f32_e32 v14, v18, v17
	v_fmamk_f32 v20, v19, 0x3e9b6dac, v5
	v_sub_f32_e32 v14, v15, v14
	v_add_f32_e32 v15, v21, v22
	v_fmaak_f32 v20, v19, v20, 0x3f2aaada
	v_sub_f32_e32 v17, v15, v21
	v_ldexp_f32 v21, v18, 1
	v_mul_f32_e32 v18, v18, v19
	v_mul_f32_e32 v18, v18, v20
	v_add_f32_e32 v19, v21, v18
	v_sub_f32_e32 v20, v19, v21
	v_ldexp_f32 v14, v14, 1
	v_sub_f32_e32 v18, v18, v20
	v_add_f32_e32 v14, v14, v18
	v_add_f32_e32 v18, v19, v14
	v_sub_f32_e32 v19, v18, v19
	v_sub_f32_e32 v14, v14, v19
	v_add_f32_e32 v19, v15, v18
	v_sub_f32_e32 v20, v19, v15
	v_sub_f32_e32 v21, v19, v20
	v_sub_f32_e32 v17, v22, v17
	v_sub_f32_e32 v15, v15, v21
	v_sub_f32_e32 v18, v18, v20
	v_add_f32_e32 v15, v18, v15
	v_add_f32_e32 v18, v17, v14
	v_sub_f32_e32 v20, v18, v17
	v_sub_f32_e32 v21, v18, v20
	v_sub_f32_e32 v17, v17, v21
	v_sub_f32_e32 v14, v14, v20
	v_add_f32_e32 v15, v18, v15
	v_add_f32_e32 v14, v14, v17
	v_add_f32_e32 v17, v19, v15
	v_sub_f32_e32 v18, v17, v19
	v_sub_f32_e32 v15, v15, v18
	v_add_f32_e32 v14, v14, v15
	v_mul_f32_e64 v15, |v9|, s4
	v_add_f32_e32 v14, v17, v14
	v_fma_f32 v17, |v9|, s4, -v15
	v_rndne_f32_e32 v18, v15
	v_fma_f32 v17, |v9|, s7, v17
	v_sub_f32_e32 v15, v15, v18
	v_add_f32_e32 v15, v15, v17
	v_exp_f32_e32 v15, v15
	v_cvt_i32_f32_e32 v17, v18
	v_cmp_neq_f32_e32 vcc, s1, v12
	s_nop 1
	v_cndmask_b32_e32 v14, v3, v14, vcc
	v_cmp_lt_f32_e64 vcc, |v12|, s8
	s_nop 1
	v_cndmask_b32_e32 v12, v14, v12, vcc
	v_ldexp_f32 v14, v15, v17
	v_cmp_ngt_f32_e64 vcc, |v9|, s3
	v_sub_f32_e32 v12, v16, v12
	v_min_f32_e32 v16, 0, v9
	v_cndmask_b32_e32 v14, 0, v14, vcc
	v_cmp_nlt_f32_e64 vcc, |v9|, s5
	s_nop 1
	v_cndmask_b32_e32 v9, v3, v14, vcc
	v_add_f32_e32 v17, 1.0, v9
	v_add_f32_e32 v14, -1.0, v17
	v_sub_f32_e32 v15, v14, v17
	v_add_f32_e32 v15, 1.0, v15
	v_sub_f32_e32 v14, v9, v14
	v_add_f32_e32 v18, v14, v15
	v_frexp_mant_f32_e32 v19, v17
	v_cvt_f64_f32_e32 v[14:15], v17
	v_frexp_exp_i32_f64_e32 v14, v[14:15]
	v_cmp_gt_f32_e32 vcc, s6, v19
	s_nop 1
	v_subbrev_co_u32_e32 v14, vcc, 0, v14, vcc
	v_sub_u32_e32 v15, 0, v14
	v_ldexp_f32 v17, v17, v15
	v_ldexp_f32 v15, v18, v15
	v_add_f32_e32 v18, -1.0, v17
	v_add_f32_e32 v21, 1.0, v17
	v_add_f32_e32 v19, 1.0, v18
	v_add_f32_e32 v22, -1.0, v21
	v_sub_f32_e32 v19, v17, v19
	v_sub_f32_e32 v17, v17, v22
	v_add_f32_e32 v19, v15, v19
	v_add_f32_e32 v15, v15, v17
	v_add_f32_e32 v17, v21, v15
	v_rcp_f32_e32 v22, v17
	v_add_f32_e32 v20, v18, v19
	v_sub_f32_e32 v18, v18, v20
	v_add_f32_e32 v18, v19, v18
	v_sub_f32_e32 v19, v21, v17
	v_add_f32_e32 v15, v15, v19
	v_mul_f32_e32 v19, v20, v22
	v_mul_f32_e32 v21, v17, v19
	v_fma_f32 v23, v19, v17, -v21
	v_fmac_f32_e32 v23, v19, v15
	v_add_f32_e32 v24, v21, v23
	v_sub_f32_e32 v25, v20, v24
	v_sub_f32_e32 v20, v20, v25
	v_sub_f32_e32 v21, v24, v21
	v_sub_f32_e32 v20, v20, v24
	v_add_f32_e32 v18, v18, v20
	v_sub_f32_e32 v20, v21, v23
	v_add_f32_e32 v18, v20, v18
	v_add_f32_e32 v20, v25, v18
	v_mul_f32_e32 v21, v22, v20
	v_mul_f32_e32 v23, v17, v21
	v_fma_f32 v17, v21, v17, -v23
	v_fmac_f32_e32 v17, v21, v15
	v_sub_f32_e32 v15, v25, v20
	v_add_f32_e32 v15, v18, v15
	v_add_f32_e32 v18, v23, v17
	v_sub_f32_e32 v24, v20, v18
	v_sub_f32_e32 v20, v20, v24
	v_sub_f32_e32 v23, v18, v23
	v_sub_f32_e32 v18, v20, v18
	v_add_f32_e32 v15, v15, v18
	v_sub_f32_e32 v17, v23, v17
	v_cvt_f32_i32_e32 v14, v14
	v_add_f32_e32 v15, v17, v15
	v_add_f32_e32 v17, v19, v21
	v_add_f32_e32 v15, v24, v15
	v_sub_f32_e32 v18, v17, v19
	v_mul_f32_e32 v15, v22, v15
	v_sub_f32_e32 v18, v21, v18
	v_add_f32_e32 v15, v18, v15
	v_mul_f32_e32 v21, 0x3f317218, v14
	v_add_f32_e32 v18, v17, v15
	v_fma_f32 v22, v14, s2, -v21
	v_mul_f32_e32 v19, v18, v18
	v_fmac_f32_e32 v22, 0xb102e308, v14
	v_sub_f32_e32 v14, v18, v17
	v_fmamk_f32 v20, v19, 0x3e9b6dac, v5
	v_sub_f32_e32 v14, v15, v14
	v_add_f32_e32 v15, v21, v22
	v_fmaak_f32 v20, v19, v20, 0x3f2aaada
	v_sub_f32_e32 v17, v15, v21
	v_ldexp_f32 v21, v18, 1
	v_mul_f32_e32 v18, v18, v19
	v_mul_f32_e32 v18, v18, v20
	v_add_f32_e32 v19, v21, v18
	v_sub_f32_e32 v20, v19, v21
	v_ldexp_f32 v14, v14, 1
	v_sub_f32_e32 v18, v18, v20
	v_add_f32_e32 v14, v14, v18
	v_add_f32_e32 v18, v19, v14
	v_sub_f32_e32 v19, v18, v19
	v_sub_f32_e32 v14, v14, v19
	v_add_f32_e32 v19, v15, v18
	v_sub_f32_e32 v20, v19, v15
	v_sub_f32_e32 v21, v19, v20
	v_sub_f32_e32 v17, v22, v17
	v_sub_f32_e32 v15, v15, v21
	v_sub_f32_e32 v18, v18, v20
	v_add_f32_e32 v15, v18, v15
	v_add_f32_e32 v18, v17, v14
	v_sub_f32_e32 v20, v18, v17
	v_sub_f32_e32 v21, v18, v20
	v_sub_f32_e32 v17, v17, v21
	v_sub_f32_e32 v14, v14, v20
	v_add_f32_e32 v15, v18, v15
	v_add_f32_e32 v14, v14, v17
	v_add_f32_e32 v17, v19, v15
	v_sub_f32_e32 v18, v17, v19
	v_sub_f32_e32 v15, v15, v18
	v_add_f32_e32 v14, v14, v15
	v_mul_f32_e64 v15, |v7|, s4
	v_add_f32_e32 v14, v17, v14
	v_fma_f32 v17, |v7|, s4, -v15
	v_rndne_f32_e32 v18, v15
	v_fma_f32 v17, |v7|, s7, v17
	v_sub_f32_e32 v15, v15, v18
	v_add_f32_e32 v15, v15, v17
	v_exp_f32_e32 v15, v15
	v_cvt_i32_f32_e32 v17, v18
	v_cmp_neq_f32_e32 vcc, s1, v9
	s_nop 1
	v_cndmask_b32_e32 v14, v3, v14, vcc
	v_cmp_lt_f32_e64 vcc, |v9|, s8
	s_nop 1
	v_cndmask_b32_e32 v9, v14, v9, vcc
	v_ldexp_f32 v14, v15, v17
	v_cmp_ngt_f32_e64 vcc, |v7|, s3
	v_sub_f32_e32 v16, v16, v9
	v_min_f32_e32 v9, 0, v7
	v_cndmask_b32_e32 v14, 0, v14, vcc
	v_cmp_nlt_f32_e64 vcc, |v7|, s5
	s_nop 1
	v_cndmask_b32_e32 v7, v3, v14, vcc
	v_add_f32_e32 v17, 1.0, v7
	v_add_f32_e32 v14, -1.0, v17
	v_sub_f32_e32 v15, v14, v17
	v_add_f32_e32 v15, 1.0, v15
	v_sub_f32_e32 v14, v7, v14
	v_add_f32_e32 v18, v14, v15
	v_frexp_mant_f32_e32 v19, v17
	v_cvt_f64_f32_e32 v[14:15], v17
	v_frexp_exp_i32_f64_e32 v14, v[14:15]
	v_cmp_gt_f32_e32 vcc, s6, v19
	s_nop 1
	v_subbrev_co_u32_e32 v14, vcc, 0, v14, vcc
	v_sub_u32_e32 v15, 0, v14
	v_ldexp_f32 v17, v17, v15
	v_ldexp_f32 v15, v18, v15
	v_add_f32_e32 v18, -1.0, v17
	v_add_f32_e32 v21, 1.0, v17
	v_add_f32_e32 v19, 1.0, v18
	v_add_f32_e32 v22, -1.0, v21
	v_sub_f32_e32 v19, v17, v19
	v_sub_f32_e32 v17, v17, v22
	v_add_f32_e32 v19, v15, v19
	v_add_f32_e32 v15, v15, v17
	v_add_f32_e32 v17, v21, v15
	v_rcp_f32_e32 v22, v17
	v_add_f32_e32 v20, v18, v19
	v_sub_f32_e32 v18, v18, v20
	v_add_f32_e32 v18, v19, v18
	v_sub_f32_e32 v19, v21, v17
	v_add_f32_e32 v15, v15, v19
	v_mul_f32_e32 v19, v20, v22
	v_mul_f32_e32 v21, v17, v19
	v_fma_f32 v23, v19, v17, -v21
	v_fmac_f32_e32 v23, v19, v15
	v_add_f32_e32 v24, v21, v23
	v_sub_f32_e32 v25, v20, v24
	v_sub_f32_e32 v20, v20, v25
	v_sub_f32_e32 v21, v24, v21
	v_sub_f32_e32 v20, v20, v24
	v_add_f32_e32 v18, v18, v20
	v_sub_f32_e32 v20, v21, v23
	v_add_f32_e32 v18, v20, v18
	v_add_f32_e32 v20, v25, v18
	v_mul_f32_e32 v21, v22, v20
	v_mul_f32_e32 v23, v17, v21
	v_fma_f32 v17, v21, v17, -v23
	v_fmac_f32_e32 v17, v21, v15
	v_sub_f32_e32 v15, v25, v20
	v_add_f32_e32 v15, v18, v15
	v_add_f32_e32 v18, v23, v17
	v_sub_f32_e32 v24, v20, v18
	v_sub_f32_e32 v20, v20, v24
	v_sub_f32_e32 v23, v18, v23
	v_sub_f32_e32 v18, v20, v18
	v_add_f32_e32 v15, v15, v18
	v_sub_f32_e32 v17, v23, v17
	v_cvt_f32_i32_e32 v14, v14
	v_add_f32_e32 v15, v17, v15
	v_add_f32_e32 v17, v19, v21
	v_add_f32_e32 v15, v24, v15
	v_sub_f32_e32 v18, v17, v19
	v_mul_f32_e32 v15, v22, v15
	v_sub_f32_e32 v18, v21, v18
	v_add_f32_e32 v15, v18, v15
	v_mul_f32_e32 v21, 0x3f317218, v14
	v_add_f32_e32 v18, v17, v15
	v_fma_f32 v22, v14, s2, -v21
	v_mul_f32_e32 v19, v18, v18
	v_fmac_f32_e32 v22, 0xb102e308, v14
	v_sub_f32_e32 v14, v18, v17
	v_fmamk_f32 v20, v19, 0x3e9b6dac, v5
	v_sub_f32_e32 v14, v15, v14
	v_add_f32_e32 v15, v21, v22
	v_fmaak_f32 v20, v19, v20, 0x3f2aaada
	v_sub_f32_e32 v17, v15, v21
	v_ldexp_f32 v21, v18, 1
	v_mul_f32_e32 v18, v18, v19
	v_mul_f32_e32 v18, v18, v20
	v_add_f32_e32 v19, v21, v18
	v_sub_f32_e32 v20, v19, v21
	v_ldexp_f32 v14, v14, 1
	v_sub_f32_e32 v18, v18, v20
	v_add_f32_e32 v14, v14, v18
	v_add_f32_e32 v18, v19, v14
	v_sub_f32_e32 v19, v18, v19
	v_sub_f32_e32 v14, v14, v19
	v_add_f32_e32 v19, v15, v18
	v_sub_f32_e32 v20, v19, v15
	v_sub_f32_e32 v21, v19, v20
	v_sub_f32_e32 v17, v22, v17
	v_sub_f32_e32 v15, v15, v21
	v_sub_f32_e32 v18, v18, v20
	v_add_f32_e32 v15, v18, v15
	v_add_f32_e32 v18, v17, v14
	v_sub_f32_e32 v20, v18, v17
	v_sub_f32_e32 v21, v18, v20
	v_sub_f32_e32 v17, v17, v21
	v_sub_f32_e32 v14, v14, v20
	v_add_f32_e32 v15, v18, v15
	v_add_f32_e32 v14, v14, v17
	v_add_f32_e32 v17, v19, v15
	v_sub_f32_e32 v18, v17, v19
	v_sub_f32_e32 v15, v15, v18
	v_add_f32_e32 v14, v14, v15
	v_mul_f32_e64 v15, |v6|, s4
	v_add_f32_e32 v14, v17, v14
	v_fma_f32 v17, |v6|, s4, -v15
	v_rndne_f32_e32 v18, v15
	v_fma_f32 v17, |v6|, s7, v17
	v_sub_f32_e32 v15, v15, v18
	v_add_f32_e32 v15, v15, v17
	v_exp_f32_e32 v15, v15
	v_cvt_i32_f32_e32 v17, v18
	v_cmp_neq_f32_e32 vcc, s1, v7
	s_nop 1
	v_cndmask_b32_e32 v14, v3, v14, vcc
	v_cmp_lt_f32_e64 vcc, |v7|, s8
	s_nop 1
	v_cndmask_b32_e32 v7, v14, v7, vcc
	v_sub_f32_e32 v14, v9, v7
	v_ldexp_f32 v7, v15, v17
	v_cmp_ngt_f32_e64 vcc, |v6|, s3
	v_min_f32_e32 v9, 0, v6
	s_nop 0
	v_cndmask_b32_e32 v7, 0, v7, vcc
	v_cmp_nlt_f32_e64 vcc, |v6|, s5
	s_nop 1
	v_cndmask_b32_e32 v15, v3, v7, vcc
	v_add_f32_e32 v17, 1.0, v15
	v_add_f32_e32 v6, -1.0, v17
	v_sub_f32_e32 v7, v6, v17
	v_add_f32_e32 v7, 1.0, v7
	v_sub_f32_e32 v6, v15, v6
	v_add_f32_e32 v18, v6, v7
	v_frexp_mant_f32_e32 v19, v17
	v_cvt_f64_f32_e32 v[6:7], v17
	v_frexp_exp_i32_f64_e32 v6, v[6:7]
	v_cmp_gt_f32_e32 vcc, s6, v19
	s_nop 1
	v_subbrev_co_u32_e32 v6, vcc, 0, v6, vcc
	v_sub_u32_e32 v7, 0, v6
	v_ldexp_f32 v17, v17, v7
	v_ldexp_f32 v7, v18, v7
	v_add_f32_e32 v18, -1.0, v17
	v_add_f32_e32 v21, 1.0, v17
	v_add_f32_e32 v19, 1.0, v18
	v_add_f32_e32 v22, -1.0, v21
	v_sub_f32_e32 v19, v17, v19
	v_sub_f32_e32 v17, v17, v22
	v_add_f32_e32 v19, v7, v19
	v_add_f32_e32 v7, v7, v17
	v_add_f32_e32 v17, v21, v7
	v_rcp_f32_e32 v22, v17
	v_add_f32_e32 v20, v18, v19
	v_sub_f32_e32 v18, v18, v20
	v_add_f32_e32 v18, v19, v18
	v_sub_f32_e32 v19, v21, v17
	v_add_f32_e32 v7, v7, v19
	v_mul_f32_e32 v19, v20, v22
	v_mul_f32_e32 v21, v17, v19
	v_fma_f32 v23, v19, v17, -v21
	v_fmac_f32_e32 v23, v19, v7
	v_add_f32_e32 v24, v21, v23
	v_sub_f32_e32 v25, v20, v24
	v_sub_f32_e32 v20, v20, v25
	v_sub_f32_e32 v21, v24, v21
	v_sub_f32_e32 v20, v20, v24
	v_add_f32_e32 v18, v18, v20
	v_sub_f32_e32 v20, v21, v23
	v_add_f32_e32 v18, v20, v18
	v_add_f32_e32 v20, v25, v18
	v_mul_f32_e32 v21, v22, v20
	v_mul_f32_e32 v23, v17, v21
	v_fma_f32 v17, v21, v17, -v23
	v_fmac_f32_e32 v17, v21, v7
	v_sub_f32_e32 v7, v25, v20
	v_add_f32_e32 v7, v18, v7
	v_add_f32_e32 v18, v23, v17
	v_sub_f32_e32 v24, v20, v18
	v_sub_f32_e32 v20, v20, v24
	v_sub_f32_e32 v23, v18, v23
	v_sub_f32_e32 v18, v20, v18
	v_add_f32_e32 v7, v7, v18
	v_sub_f32_e32 v17, v23, v17
	v_add_f32_e32 v7, v17, v7
	v_add_f32_e32 v17, v19, v21
	v_add_f32_e32 v7, v24, v7
	v_sub_f32_e32 v18, v17, v19
	v_mul_f32_e32 v7, v22, v7
	v_sub_f32_e32 v18, v21, v18
	v_add_f32_e32 v7, v18, v7
	v_cvt_f32_i32_e32 v6, v6
	v_add_f32_e32 v18, v17, v7
	v_mul_f32_e32 v19, v18, v18
	v_fmac_f32_e32 v5, 0x3e9b6dac, v19
	v_fmac_f32_e32 v4, v19, v5
	v_mul_f32_e32 v5, 0x3f317218, v6
	v_fma_f32 v20, v6, s2, -v5
	v_fmac_f32_e32 v20, 0xb102e308, v6
	v_sub_f32_e32 v6, v18, v17
	v_ldexp_f32 v17, v18, 1
	v_mul_f32_e32 v18, v18, v19
	v_mul_f32_e32 v4, v18, v4
	v_add_f32_e32 v18, v17, v4
	v_sub_f32_e32 v6, v7, v6
	v_sub_f32_e32 v17, v18, v17
	v_ldexp_f32 v6, v6, 1
	v_sub_f32_e32 v4, v4, v17
	v_add_f32_e32 v4, v6, v4
	v_add_f32_e32 v6, v18, v4
	v_add_f32_e32 v7, v5, v20
	v_sub_f32_e32 v17, v6, v18
	v_sub_f32_e32 v4, v4, v17
	v_add_f32_e32 v17, v7, v6
	v_sub_f32_e32 v18, v17, v7
	v_sub_f32_e32 v5, v7, v5
	v_sub_f32_e32 v19, v17, v18
	v_sub_f32_e32 v5, v20, v5
	v_sub_f32_e32 v7, v7, v19
	v_sub_f32_e32 v6, v6, v18
	v_add_f32_e32 v6, v6, v7
	v_add_f32_e32 v7, v5, v4
	v_sub_f32_e32 v18, v7, v5
	v_sub_f32_e32 v19, v7, v18
	v_sub_f32_e32 v5, v5, v19
	v_sub_f32_e32 v4, v4, v18
	v_add_f32_e32 v4, v4, v5
	v_add_f32_e32 v5, v7, v6
	v_add_f32_e32 v6, v17, v5
	v_sub_f32_e32 v7, v6, v17
	v_sub_f32_e32 v5, v5, v7
	v_add_f32_e32 v4, v4, v5
	v_add_f32_e32 v4, v6, v4
	v_cmp_neq_f32_e32 vcc, s1, v15
	s_nop 1
	v_cndmask_b32_e32 v3, v3, v4, vcc
	v_cmp_lt_f32_e64 vcc, |v15|, s8
	s_nop 1
	v_cndmask_b32_e32 v3, v3, v15, vcc
	v_sub_f32_e32 v5, v9, v3
	v_add_f32_e32 v3, v8, v2
	v_add_f32_e32 v8, v11, v3
	v_add_f32_e32 v9, v13, v8
	v_mbcnt_lo_u32_b32 v11, -1, 0
	v_add_f32_e32 v6, v12, v9
	v_mbcnt_hi_u32_b32 v12, -1, v11
	v_and_b32_e32 v13, 64, v12
	v_add_u32_e32 v11, -1, v12
	v_add_f32_e32 v7, v16, v6
	v_cmp_lt_i32_e32 vcc, v11, v13
	v_add_f32_e32 v4, v14, v7
	v_add_f32_e32 v5, v5, v4
	v_cndmask_b32_e32 v11, v11, v12, vcc
	v_lshlrev_b32_e32 v11, 2, v11
	ds_bpermute_b32 v11, v11, v5
	v_cmp_gt_i32_e32 vcc, 1, v10
	v_add_u32_e32 v14, -2, v12
	s_waitcnt lgkmcnt(0)
	v_add_f32_e32 v11, v5, v11
	v_cndmask_b32_e32 v11, v11, v5, vcc
	v_cmp_lt_i32_e32 vcc, v14, v13
	s_nop 1
	v_cndmask_b32_e32 v14, v14, v12, vcc
	v_lshlrev_b32_e32 v14, 2, v14
	ds_bpermute_b32 v14, v14, v11
	v_cmp_gt_i32_e32 vcc, 2, v10
	s_waitcnt lgkmcnt(0)
	v_add_f32_e32 v14, v11, v14
	v_cndmask_b32_e32 v11, v14, v11, vcc
	v_add_u32_e32 v14, -4, v12
	v_cmp_lt_i32_e32 vcc, v14, v13
	s_nop 1
	v_cndmask_b32_e32 v14, v14, v12, vcc
	v_lshlrev_b32_e32 v14, 2, v14
	ds_bpermute_b32 v14, v14, v11
	v_cmp_gt_i32_e32 vcc, 4, v10
	s_waitcnt lgkmcnt(0)
	v_add_f32_e32 v14, v11, v14
	v_cndmask_b32_e32 v11, v14, v11, vcc
	v_add_u32_e32 v14, -8, v12
	v_cmp_lt_i32_e32 vcc, v14, v13
	s_nop 1
	v_cndmask_b32_e32 v14, v14, v12, vcc
	v_lshlrev_b32_e32 v14, 2, v14
	ds_bpermute_b32 v14, v14, v11
	v_cmp_gt_i32_e32 vcc, 8, v10
	s_waitcnt lgkmcnt(0)
	v_add_f32_e32 v14, v11, v14
	v_cndmask_b32_e32 v11, v14, v11, vcc
	v_add_u32_e32 v14, -16, v12
	v_cmp_lt_i32_e32 vcc, v14, v13
	s_nop 1
	v_cndmask_b32_e32 v14, v14, v12, vcc
	v_lshlrev_b32_e32 v14, 2, v14
	ds_bpermute_b32 v14, v14, v11
	v_cmp_gt_i32_e32 vcc, 16, v10
	s_waitcnt lgkmcnt(0)
	v_add_f32_e32 v14, v11, v14
	v_cndmask_b32_e32 v11, v14, v11, vcc
	v_subrev_u32_e32 v14, 32, v12
	v_cmp_lt_i32_e32 vcc, v14, v13
	s_nop 1
	v_cndmask_b32_e32 v12, v14, v12, vcc
	v_lshlrev_b32_e32 v12, 2, v12
	ds_bpermute_b32 v12, v12, v11
	v_cmp_eq_u32_e32 vcc, 63, v10
	s_waitcnt lgkmcnt(0)
	v_add_f32_e32 v12, v11, v12
	s_and_saveexec_b64 s[2:3], vcc
	s_lshl_b32 s1, s69, 2
	s_add_i32 s1, s1, 0
	s_add_i32 s1, s1, 0x27f80
	v_mov_b32_e32 v13, s1
	ds_write_b32 v13, v12
	s_or_b64 exec, exec, s[2:3]
	v_cmp_gt_i32_e32 vcc, 32, v10
	s_cmp_lt_u32 s68, 64
	s_waitcnt lgkmcnt(0)
	v_cndmask_b32_e32 v10, v12, v11, vcc
	v_sub_f32_e32 v10, v10, v5
	s_barrier
	s_cbranch_scc1 .LBB0_383
	s_add_i32 s1, s69, -1
	s_cmp_lt_u32 s1, 7
	s_cbranch_scc1 .LBB0_380
	s_mov_b32 s2, 0
	s_add_i32 s3, 0, 0x27f80
	s_and_b32 s1, s69, 0x3fffff8

.Lscan_hook:
	s_cmpk_ge_i32 s76, 32
	s_cbranch_scc1 .LBB0_458
	v_cmp_eq_u32_e32 vcc, 0, v161
	s_and_saveexec_b64 s[2:3], vcc
	s_cbranch_execz .Lscan_wait_done
	v_mov_b32_e32 v0, 0x3900
	s_mov_b32 s4, 0
